# v094 + u-sweep loops: last row of buffer B waits vmcnt(8) instead of 0 (the refill of buffer A stays in flight into the next iteration)
# baseline (speedup 1.0000x reference)
.LBB0_889:
	s_waitcnt vmcnt(15)
	v_cvt_scalef32_pk_f32_fp4 v[112:113], v60, 1.0
	v_pk_fma_f32 v[112:113], v[112:113], v[64:65], 0 op_sel_hi:[1,1,0]
	v_cvt_scalef32_pk_f32_fp4 v[114:115], v60, 1.0 op_sel:[1,0,0]
	v_pk_fma_f32 v[112:113], v[114:115], v[66:67], v[112:113]
	v_cvt_scalef32_pk_f32_fp4 v[114:115], v60, 1.0 op_sel:[0,1,0]
	v_pk_fma_f32 v[112:113], v[114:115], v[68:69], v[112:113]
	v_cvt_scalef32_pk_f32_fp4 v[114:115], v60, 1.0 op_sel:[1,1,0]
	v_pk_fma_f32 v[112:113], v[114:115], v[70:71], v[112:113]
	v_cvt_scalef32_pk_f32_fp4 v[114:115], v61, 1.0
	v_pk_fma_f32 v[112:113], v[114:115], v[72:73], v[112:113]
	v_cvt_scalef32_pk_f32_fp4 v[114:115], v61, 1.0 op_sel:[1,0,0]
	v_pk_fma_f32 v[112:113], v[114:115], v[74:75], v[112:113]
	v_cvt_scalef32_pk_f32_fp4 v[114:115], v61, 1.0 op_sel:[0,1,0]
	v_pk_fma_f32 v[112:113], v[114:115], v[76:77], v[112:113]
	v_cvt_scalef32_pk_f32_fp4 v[60:61], v61, 1.0 op_sel:[1,1,0]
	v_pk_fma_f32 v[60:61], v[60:61], v[78:79], v[112:113]
	v_cvt_scalef32_pk_f32_fp4 v[112:113], v62, 1.0
	v_pk_fma_f32 v[60:61], v[112:113], v[80:81], v[60:61]
	v_cvt_scalef32_pk_f32_fp4 v[112:113], v62, 1.0 op_sel:[1,0,0]
	v_pk_fma_f32 v[60:61], v[112:113], v[82:83], v[60:61]
	v_cvt_scalef32_pk_f32_fp4 v[112:113], v62, 1.0 op_sel:[0,1,0]
	v_pk_fma_f32 v[60:61], v[112:113], v[84:85], v[60:61]
	v_cvt_scalef32_pk_f32_fp4 v[112:113], v62, 1.0 op_sel:[1,1,0]
	v_pk_fma_f32 v[60:61], v[112:113], v[86:87], v[60:61]
	v_cvt_scalef32_pk_f32_fp4 v[112:113], v63, 1.0
	v_pk_fma_f32 v[60:61], v[112:113], v[88:89], v[60:61]
	v_cvt_scalef32_pk_f32_fp4 v[112:113], v63, 1.0 op_sel:[1,0,0]
	v_pk_fma_f32 v[60:61], v[112:113], v[90:91], v[60:61]
	v_cvt_scalef32_pk_f32_fp4 v[112:113], v63, 1.0 op_sel:[0,1,0]
	v_pk_fma_f32 v[60:61], v[112:113], v[92:93], v[60:61]
	v_cvt_scalef32_pk_f32_fp4 v[62:63], v63, 1.0 op_sel:[1,1,0]
	v_pk_fma_f32 v[60:61], v[62:63], v[94:95], v[60:61]
	s_waitcnt vmcnt(14)
	v_cvt_scalef32_pk_f32_fp4 v[62:63], v52, 1.0 op_sel:[1,0,0]
	v_add_f32_e32 v112, v60, v61
	v_cvt_scalef32_pk_f32_fp4 v[60:61], v52, 1.0
	v_pk_fma_f32 v[60:61], v[60:61], v[64:65], 0 op_sel_hi:[1,1,0]
	v_cmp_eq_u32_e32 vcc, s10, v148
	v_pk_fma_f32 v[60:61], v[62:63], v[66:67], v[60:61]
	v_cvt_scalef32_pk_f32_fp4 v[62:63], v52, 1.0 op_sel:[0,1,0]
	v_pk_fma_f32 v[60:61], v[62:63], v[68:69], v[60:61]
	v_cvt_scalef32_pk_f32_fp4 v[62:63], v52, 1.0 op_sel:[1,1,0]
	v_pk_fma_f32 v[60:61], v[62:63], v[70:71], v[60:61]
	v_cvt_scalef32_pk_f32_fp4 v[62:63], v53, 1.0
	v_pk_fma_f32 v[60:61], v[62:63], v[72:73], v[60:61]
	v_cvt_scalef32_pk_f32_fp4 v[62:63], v53, 1.0 op_sel:[1,0,0]
	v_pk_fma_f32 v[60:61], v[62:63], v[74:75], v[60:61]
	v_cvt_scalef32_pk_f32_fp4 v[62:63], v53, 1.0 op_sel:[0,1,0]
	v_pk_fma_f32 v[60:61], v[62:63], v[76:77], v[60:61]
	v_cvt_scalef32_pk_f32_fp4 v[52:53], v53, 1.0 op_sel:[1,1,0]
	v_pk_fma_f32 v[52:53], v[52:53], v[78:79], v[60:61]
	v_cvt_scalef32_pk_f32_fp4 v[60:61], v54, 1.0
	v_pk_fma_f32 v[52:53], v[60:61], v[80:81], v[52:53]
	v_cvt_scalef32_pk_f32_fp4 v[60:61], v54, 1.0 op_sel:[1,0,0]
	v_pk_fma_f32 v[52:53], v[60:61], v[82:83], v[52:53]
	v_cvt_scalef32_pk_f32_fp4 v[60:61], v54, 1.0 op_sel:[0,1,0]
	v_pk_fma_f32 v[52:53], v[60:61], v[84:85], v[52:53]
	v_cvt_scalef32_pk_f32_fp4 v[60:61], v54, 1.0 op_sel:[1,1,0]
	v_pk_fma_f32 v[52:53], v[60:61], v[86:87], v[52:53]
	v_cvt_scalef32_pk_f32_fp4 v[60:61], v55, 1.0
	v_pk_fma_f32 v[52:53], v[60:61], v[88:89], v[52:53]
	v_cvt_scalef32_pk_f32_fp4 v[60:61], v55, 1.0 op_sel:[1,0,0]
	v_pk_fma_f32 v[52:53], v[60:61], v[90:91], v[52:53]
	v_cvt_scalef32_pk_f32_fp4 v[60:61], v55, 1.0 op_sel:[0,1,0]
	v_pk_fma_f32 v[52:53], v[60:61], v[92:93], v[52:53]
	v_cvt_scalef32_pk_f32_fp4 v[54:55], v55, 1.0 op_sel:[1,1,0]
	v_pk_fma_f32 v[52:53], v[54:55], v[94:95], v[52:53]
	s_waitcnt vmcnt(13)
	v_cvt_scalef32_pk_f32_fp4 v[54:55], v48, 1.0 op_sel:[1,0,0]
	v_add_f32_e32 v60, v52, v53
	v_cvt_scalef32_pk_f32_fp4 v[52:53], v48, 1.0
	v_pk_fma_f32 v[52:53], v[52:53], v[64:65], 0 op_sel_hi:[1,1,0]
	s_nop 0
	v_pk_fma_f32 v[52:53], v[54:55], v[66:67], v[52:53]
	v_cvt_scalef32_pk_f32_fp4 v[54:55], v48, 1.0 op_sel:[0,1,0]
	v_pk_fma_f32 v[52:53], v[54:55], v[68:69], v[52:53]
	v_cvt_scalef32_pk_f32_fp4 v[54:55], v48, 1.0 op_sel:[1,1,0]
	v_pk_fma_f32 v[52:53], v[54:55], v[70:71], v[52:53]
	v_cvt_scalef32_pk_f32_fp4 v[54:55], v49, 1.0
	v_pk_fma_f32 v[52:53], v[54:55], v[72:73], v[52:53]
	v_cvt_scalef32_pk_f32_fp4 v[54:55], v49, 1.0 op_sel:[1,0,0]
	v_pk_fma_f32 v[52:53], v[54:55], v[74:75], v[52:53]
	v_cvt_scalef32_pk_f32_fp4 v[54:55], v49, 1.0 op_sel:[0,1,0]
	v_pk_fma_f32 v[52:53], v[54:55], v[76:77], v[52:53]
	v_cvt_scalef32_pk_f32_fp4 v[48:49], v49, 1.0 op_sel:[1,1,0]
	v_pk_fma_f32 v[48:49], v[48:49], v[78:79], v[52:53]
	v_cvt_scalef32_pk_f32_fp4 v[52:53], v50, 1.0
	v_pk_fma_f32 v[48:49], v[52:53], v[80:81], v[48:49]
	v_cvt_scalef32_pk_f32_fp4 v[52:53], v50, 1.0 op_sel:[1,0,0]
	v_pk_fma_f32 v[48:49], v[52:53], v[82:83], v[48:49]
	v_cvt_scalef32_pk_f32_fp4 v[52:53], v50, 1.0 op_sel:[0,1,0]
	v_pk_fma_f32 v[48:49], v[52:53], v[84:85], v[48:49]
	v_cvt_scalef32_pk_f32_fp4 v[52:53], v50, 1.0 op_sel:[1,1,0]
	v_pk_fma_f32 v[48:49], v[52:53], v[86:87], v[48:49]
	v_cvt_scalef32_pk_f32_fp4 v[52:53], v51, 1.0
	v_pk_fma_f32 v[48:49], v[52:53], v[88:89], v[48:49]
	v_cvt_scalef32_pk_f32_fp4 v[52:53], v51, 1.0 op_sel:[1,0,0]
	v_pk_fma_f32 v[48:49], v[52:53], v[90:91], v[48:49]
	v_cvt_scalef32_pk_f32_fp4 v[52:53], v51, 1.0 op_sel:[0,1,0]
	v_pk_fma_f32 v[48:49], v[52:53], v[92:93], v[48:49]
	v_cvt_scalef32_pk_f32_fp4 v[50:51], v51, 1.0 op_sel:[1,1,0]
	v_pk_fma_f32 v[48:49], v[50:51], v[94:95], v[48:49]
	s_waitcnt vmcnt(12)
	v_cvt_scalef32_pk_f32_fp4 v[50:51], v40, 1.0 op_sel:[1,0,0]
	v_add_f32_e32 v52, v48, v49
	v_cvt_scalef32_pk_f32_fp4 v[48:49], v40, 1.0
	v_pk_fma_f32 v[48:49], v[48:49], v[64:65], 0 op_sel_hi:[1,1,0]
	s_nop 0
	v_pk_fma_f32 v[48:49], v[50:51], v[66:67], v[48:49]
	v_cvt_scalef32_pk_f32_fp4 v[50:51], v40, 1.0 op_sel:[0,1,0]
	v_pk_fma_f32 v[48:49], v[50:51], v[68:69], v[48:49]
	v_cvt_scalef32_pk_f32_fp4 v[50:51], v40, 1.0 op_sel:[1,1,0]
	v_pk_fma_f32 v[48:49], v[50:51], v[70:71], v[48:49]
	v_cvt_scalef32_pk_f32_fp4 v[50:51], v41, 1.0
	v_pk_fma_f32 v[48:49], v[50:51], v[72:73], v[48:49]
	v_cvt_scalef32_pk_f32_fp4 v[50:51], v41, 1.0 op_sel:[1,0,0]
	v_pk_fma_f32 v[48:49], v[50:51], v[74:75], v[48:49]
	v_cvt_scalef32_pk_f32_fp4 v[50:51], v41, 1.0 op_sel:[0,1,0]
	v_pk_fma_f32 v[48:49], v[50:51], v[76:77], v[48:49]
	v_cvt_scalef32_pk_f32_fp4 v[40:41], v41, 1.0 op_sel:[1,1,0]
	v_pk_fma_f32 v[40:41], v[40:41], v[78:79], v[48:49]
	v_cvt_scalef32_pk_f32_fp4 v[48:49], v42, 1.0
	v_pk_fma_f32 v[40:41], v[48:49], v[80:81], v[40:41]
	v_cvt_scalef32_pk_f32_fp4 v[48:49], v42, 1.0 op_sel:[1,0,0]
	v_pk_fma_f32 v[40:41], v[48:49], v[82:83], v[40:41]
	v_cvt_scalef32_pk_f32_fp4 v[48:49], v42, 1.0 op_sel:[0,1,0]
	v_pk_fma_f32 v[40:41], v[48:49], v[84:85], v[40:41]
	v_cvt_scalef32_pk_f32_fp4 v[48:49], v42, 1.0 op_sel:[1,1,0]
	v_pk_fma_f32 v[40:41], v[48:49], v[86:87], v[40:41]
	v_cvt_scalef32_pk_f32_fp4 v[48:49], v43, 1.0
	v_pk_fma_f32 v[40:41], v[48:49], v[88:89], v[40:41]
	v_cvt_scalef32_pk_f32_fp4 v[48:49], v43, 1.0 op_sel:[1,0,0]
	v_pk_fma_f32 v[40:41], v[48:49], v[90:91], v[40:41]
	v_cvt_scalef32_pk_f32_fp4 v[48:49], v43, 1.0 op_sel:[0,1,0]
	v_pk_fma_f32 v[40:41], v[48:49], v[92:93], v[40:41]
	v_cvt_scalef32_pk_f32_fp4 v[42:43], v43, 1.0 op_sel:[1,1,0]
	v_pk_fma_f32 v[40:41], v[42:43], v[94:95], v[40:41]
	v_cndmask_b32_e64 v43, v52, v112, s[0:1]
	v_add_f32_e32 v40, v40, v41
	v_cndmask_b32_e64 v41, v112, v52, s[0:1]
	v_cndmask_b32_e64 v42, v60, v40, s[0:1]
	ds_bpermute_b32 v41, v129, v41
	ds_bpermute_b32 v42, v129, v42
	v_cndmask_b32_e64 v40, v40, v60, s[0:1]
	s_waitcnt lgkmcnt(3)
	v_cndmask_b32_e32 v48, v107, v111, vcc
	v_cmp_eq_u32_e32 vcc, s10, v151
	s_waitcnt lgkmcnt(1)
	v_add_f32_e32 v41, v43, v41
	s_waitcnt lgkmcnt(0)
	v_add_f32_e32 v40, v40, v42
	v_cndmask_b32_e64 v42, v41, v40, s[2:3]
	ds_bpermute_b32 v42, v146, v42
	v_cndmask_b32_e64 v40, v40, v41, s[2:3]
	s_waitcnt lgkmcnt(0)
	v_add_f32_e32 v40, v40, v42
	s_nop 1
	v_add_f32_dpp v49, v40, v40 quad_perm:[1,0,3,2] row_mask:0xf bank_mask:0xf bound_ctrl:1
	s_waitcnt vmcnt(11)
	v_cvt_scalef32_pk_f32_fp4 v[40:41], v36, 1.0
	v_pk_fma_f32 v[40:41], v[40:41], v[64:65], 0 op_sel_hi:[1,1,0]
	v_cvt_scalef32_pk_f32_fp4 v[42:43], v36, 1.0 op_sel:[1,0,0]
	v_pk_fma_f32 v[40:41], v[42:43], v[66:67], v[40:41]
	v_cvt_scalef32_pk_f32_fp4 v[42:43], v36, 1.0 op_sel:[0,1,0]
	v_pk_fma_f32 v[40:41], v[42:43], v[68:69], v[40:41]
	v_cvt_scalef32_pk_f32_fp4 v[42:43], v36, 1.0 op_sel:[1,1,0]
	v_pk_fma_f32 v[40:41], v[42:43], v[70:71], v[40:41]
	v_cvt_scalef32_pk_f32_fp4 v[42:43], v37, 1.0
	v_pk_fma_f32 v[40:41], v[42:43], v[72:73], v[40:41]
	v_cvt_scalef32_pk_f32_fp4 v[42:43], v37, 1.0 op_sel:[1,0,0]
	v_pk_fma_f32 v[40:41], v[42:43], v[74:75], v[40:41]
	v_cvt_scalef32_pk_f32_fp4 v[42:43], v37, 1.0 op_sel:[0,1,0]
	v_pk_fma_f32 v[40:41], v[42:43], v[76:77], v[40:41]
	v_cvt_scalef32_pk_f32_fp4 v[36:37], v37, 1.0 op_sel:[1,1,0]
	v_pk_fma_f32 v[36:37], v[36:37], v[78:79], v[40:41]
	v_cvt_scalef32_pk_f32_fp4 v[40:41], v38, 1.0
	v_pk_fma_f32 v[36:37], v[40:41], v[80:81], v[36:37]
	v_cvt_scalef32_pk_f32_fp4 v[40:41], v38, 1.0 op_sel:[1,0,0]
	v_pk_fma_f32 v[36:37], v[40:41], v[82:83], v[36:37]
	v_cvt_scalef32_pk_f32_fp4 v[40:41], v38, 1.0 op_sel:[0,1,0]
	v_pk_fma_f32 v[36:37], v[40:41], v[84:85], v[36:37]
	v_cvt_scalef32_pk_f32_fp4 v[40:41], v38, 1.0 op_sel:[1,1,0]
	v_pk_fma_f32 v[36:37], v[40:41], v[86:87], v[36:37]
	v_cvt_scalef32_pk_f32_fp4 v[40:41], v39, 1.0
	v_pk_fma_f32 v[36:37], v[40:41], v[88:89], v[36:37]
	v_cvt_scalef32_pk_f32_fp4 v[40:41], v39, 1.0 op_sel:[1,0,0]
	v_pk_fma_f32 v[36:37], v[40:41], v[90:91], v[36:37]
	v_cvt_scalef32_pk_f32_fp4 v[40:41], v39, 1.0 op_sel:[0,1,0]
	v_pk_fma_f32 v[36:37], v[40:41], v[92:93], v[36:37]
	v_cvt_scalef32_pk_f32_fp4 v[38:39], v39, 1.0 op_sel:[1,1,0]
	v_pk_fma_f32 v[36:37], v[38:39], v[94:95], v[36:37]
	s_waitcnt vmcnt(10)
	v_cvt_scalef32_pk_f32_fp4 v[38:39], v32, 1.0 op_sel:[1,0,0]
	v_add_f32_e32 v40, v36, v37
	v_cvt_scalef32_pk_f32_fp4 v[36:37], v32, 1.0
	v_pk_fma_f32 v[36:37], v[36:37], v[64:65], 0 op_sel_hi:[1,1,0]
	s_nop 0
	v_pk_fma_f32 v[36:37], v[38:39], v[66:67], v[36:37]
	v_cvt_scalef32_pk_f32_fp4 v[38:39], v32, 1.0 op_sel:[0,1,0]
	v_pk_fma_f32 v[36:37], v[38:39], v[68:69], v[36:37]
	v_cvt_scalef32_pk_f32_fp4 v[38:39], v32, 1.0 op_sel:[1,1,0]
	v_pk_fma_f32 v[36:37], v[38:39], v[70:71], v[36:37]
	v_cvt_scalef32_pk_f32_fp4 v[38:39], v33, 1.0
	v_pk_fma_f32 v[36:37], v[38:39], v[72:73], v[36:37]
	v_cvt_scalef32_pk_f32_fp4 v[38:39], v33, 1.0 op_sel:[1,0,0]
	v_pk_fma_f32 v[36:37], v[38:39], v[74:75], v[36:37]
	v_cvt_scalef32_pk_f32_fp4 v[38:39], v33, 1.0 op_sel:[0,1,0]
	v_pk_fma_f32 v[36:37], v[38:39], v[76:77], v[36:37]
	v_cvt_scalef32_pk_f32_fp4 v[32:33], v33, 1.0 op_sel:[1,1,0]
	v_pk_fma_f32 v[32:33], v[32:33], v[78:79], v[36:37]
	v_cvt_scalef32_pk_f32_fp4 v[36:37], v34, 1.0
	v_pk_fma_f32 v[32:33], v[36:37], v[80:81], v[32:33]
	v_cvt_scalef32_pk_f32_fp4 v[36:37], v34, 1.0 op_sel:[1,0,0]
	v_pk_fma_f32 v[32:33], v[36:37], v[82:83], v[32:33]
	v_cvt_scalef32_pk_f32_fp4 v[36:37], v34, 1.0 op_sel:[0,1,0]
	v_pk_fma_f32 v[32:33], v[36:37], v[84:85], v[32:33]
	v_cvt_scalef32_pk_f32_fp4 v[36:37], v34, 1.0 op_sel:[1,1,0]
	v_pk_fma_f32 v[32:33], v[36:37], v[86:87], v[32:33]
	v_cvt_scalef32_pk_f32_fp4 v[36:37], v35, 1.0
	v_pk_fma_f32 v[32:33], v[36:37], v[88:89], v[32:33]
	v_cvt_scalef32_pk_f32_fp4 v[36:37], v35, 1.0 op_sel:[1,0,0]
	v_pk_fma_f32 v[32:33], v[36:37], v[90:91], v[32:33]
	v_cvt_scalef32_pk_f32_fp4 v[36:37], v35, 1.0 op_sel:[0,1,0]
	v_pk_fma_f32 v[32:33], v[36:37], v[92:93], v[32:33]
	v_cvt_scalef32_pk_f32_fp4 v[34:35], v35, 1.0 op_sel:[1,1,0]
	v_pk_fma_f32 v[32:33], v[34:35], v[94:95], v[32:33]
	s_waitcnt vmcnt(9)
; #define PU_LOAD(BUF, EV, S0) do { _Pragma("unroll") for (int i = 0; i < 8; ++i) { const int row_ = __builtin_amdgcn_readlane(EV, (S0) + i); BUF[i & 3][i >> 2] = *(const u32x4*)(PU8 + (size_t)row_ * 1024 + lane * 16); } } while (0)
; __global__ void __launch_bounds__(NT, 2) mk_fwd(Args args) {
;     ...
;                 for (int s = 0; s < 64; s += 16) {
;                     PU_LOAD(bB, ev, s + 8);
;                     PU_DOT4(bA, 0, s); PU_DOT4(bA, 1, s + 4);
;                     if (s + 16 < 64) PU_LOAD(bA, ev, s + 16);
;                     PU_DOT4(bB, 0, s + 8); PU_DOT4(bB, 1, s + 12);
;                 }
	v_cvt_scalef32_pk_f32_fp4 v[34:35], v56, 1.0 op_sel:[1,0,0]
	v_add_f32_e32 v36, v32, v33
	v_cvt_scalef32_pk_f32_fp4 v[32:33], v56, 1.0
	v_pk_fma_f32 v[32:33], v[32:33], v[64:65], 0 op_sel_hi:[1,1,0]
	s_nop 0
	v_pk_fma_f32 v[32:33], v[34:35], v[66:67], v[32:33]
	v_cvt_scalef32_pk_f32_fp4 v[34:35], v56, 1.0 op_sel:[0,1,0]
	v_pk_fma_f32 v[32:33], v[34:35], v[68:69], v[32:33]
	v_cvt_scalef32_pk_f32_fp4 v[34:35], v56, 1.0 op_sel:[1,1,0]
	v_pk_fma_f32 v[32:33], v[34:35], v[70:71], v[32:33]
	v_cvt_scalef32_pk_f32_fp4 v[34:35], v57, 1.0
	v_pk_fma_f32 v[32:33], v[34:35], v[72:73], v[32:33]
	v_cvt_scalef32_pk_f32_fp4 v[34:35], v57, 1.0 op_sel:[1,0,0]
	v_pk_fma_f32 v[32:33], v[34:35], v[74:75], v[32:33]
	v_cvt_scalef32_pk_f32_fp4 v[34:35], v57, 1.0 op_sel:[0,1,0]
	v_pk_fma_f32 v[32:33], v[34:35], v[76:77], v[32:33]
	v_cvt_scalef32_pk_f32_fp4 v[34:35], v57, 1.0 op_sel:[1,1,0]
	v_pk_fma_f32 v[32:33], v[34:35], v[78:79], v[32:33]
	v_cvt_scalef32_pk_f32_fp4 v[34:35], v58, 1.0
	v_pk_fma_f32 v[32:33], v[34:35], v[80:81], v[32:33]
	v_cvt_scalef32_pk_f32_fp4 v[34:35], v58, 1.0 op_sel:[1,0,0]
	v_pk_fma_f32 v[32:33], v[34:35], v[82:83], v[32:33]
	v_cvt_scalef32_pk_f32_fp4 v[34:35], v58, 1.0 op_sel:[0,1,0]
	v_pk_fma_f32 v[32:33], v[34:35], v[84:85], v[32:33]
	v_cvt_scalef32_pk_f32_fp4 v[34:35], v58, 1.0 op_sel:[1,1,0]
	v_pk_fma_f32 v[32:33], v[34:35], v[86:87], v[32:33]
	v_cvt_scalef32_pk_f32_fp4 v[34:35], v59, 1.0
	v_pk_fma_f32 v[32:33], v[34:35], v[88:89], v[32:33]
	v_cvt_scalef32_pk_f32_fp4 v[34:35], v59, 1.0 op_sel:[1,0,0]
	v_pk_fma_f32 v[32:33], v[34:35], v[90:91], v[32:33]
	v_cvt_scalef32_pk_f32_fp4 v[34:35], v59, 1.0 op_sel:[0,1,0]
	v_pk_fma_f32 v[32:33], v[34:35], v[92:93], v[32:33]
	v_cvt_scalef32_pk_f32_fp4 v[34:35], v59, 1.0 op_sel:[1,1,0]
	v_pk_fma_f32 v[32:33], v[34:35], v[94:95], v[32:33]
	s_waitcnt vmcnt(8)
	v_cvt_scalef32_pk_f32_fp4 v[34:35], v44, 1.0 op_sel:[1,0,0]
	v_add_f32_e32 v37, v32, v33
	v_cvt_scalef32_pk_f32_fp4 v[32:33], v44, 1.0
	v_pk_fma_f32 v[32:33], v[32:33], v[64:65], 0 op_sel_hi:[1,1,0]
	s_nop 0
	v_pk_fma_f32 v[32:33], v[34:35], v[66:67], v[32:33]
	v_cvt_scalef32_pk_f32_fp4 v[34:35], v44, 1.0 op_sel:[0,1,0]
	v_pk_fma_f32 v[32:33], v[34:35], v[68:69], v[32:33]
	v_cvt_scalef32_pk_f32_fp4 v[34:35], v44, 1.0 op_sel:[1,1,0]
	v_pk_fma_f32 v[32:33], v[34:35], v[70:71], v[32:33]
	v_cvt_scalef32_pk_f32_fp4 v[34:35], v45, 1.0
	v_pk_fma_f32 v[32:33], v[34:35], v[72:73], v[32:33]
	v_cvt_scalef32_pk_f32_fp4 v[34:35], v45, 1.0 op_sel:[1,0,0]
	v_pk_fma_f32 v[32:33], v[34:35], v[74:75], v[32:33]
	v_cvt_scalef32_pk_f32_fp4 v[34:35], v45, 1.0 op_sel:[0,1,0]
	v_pk_fma_f32 v[32:33], v[34:35], v[76:77], v[32:33]
	v_cvt_scalef32_pk_f32_fp4 v[34:35], v45, 1.0 op_sel:[1,1,0]
	v_pk_fma_f32 v[32:33], v[34:35], v[78:79], v[32:33]
	v_cvt_scalef32_pk_f32_fp4 v[34:35], v46, 1.0
	v_pk_fma_f32 v[32:33], v[34:35], v[80:81], v[32:33]
	v_cvt_scalef32_pk_f32_fp4 v[34:35], v46, 1.0 op_sel:[1,0,0]
	v_pk_fma_f32 v[32:33], v[34:35], v[82:83], v[32:33]
	v_cvt_scalef32_pk_f32_fp4 v[34:35], v46, 1.0 op_sel:[0,1,0]
	v_pk_fma_f32 v[32:33], v[34:35], v[84:85], v[32:33]
	v_cvt_scalef32_pk_f32_fp4 v[34:35], v46, 1.0 op_sel:[1,1,0]
	v_pk_fma_f32 v[32:33], v[34:35], v[86:87], v[32:33]
	v_cvt_scalef32_pk_f32_fp4 v[34:35], v47, 1.0
	v_pk_fma_f32 v[32:33], v[34:35], v[88:89], v[32:33]
	v_cvt_scalef32_pk_f32_fp4 v[34:35], v47, 1.0 op_sel:[1,0,0]
	v_pk_fma_f32 v[32:33], v[34:35], v[90:91], v[32:33]
	v_cvt_scalef32_pk_f32_fp4 v[34:35], v47, 1.0 op_sel:[0,1,0]
	v_pk_fma_f32 v[32:33], v[34:35], v[92:93], v[32:33]
	v_cvt_scalef32_pk_f32_fp4 v[34:35], v47, 1.0 op_sel:[1,1,0]
	v_pk_fma_f32 v[32:33], v[34:35], v[94:95], v[32:33]
	s_nop 0
	v_add_f32_e32 v32, v32, v33
	v_cndmask_b32_e64 v33, v40, v37, s[0:1]
	v_cndmask_b32_e64 v34, v36, v32, s[0:1]
	ds_bpermute_b32 v33, v129, v33
	ds_bpermute_b32 v34, v129, v34
	v_cndmask_b32_e64 v37, v37, v40, s[0:1]
	v_cndmask_b32_e64 v32, v32, v36, s[0:1]
	v_add_f32_dpp v35, v49, v49 quad_perm:[2,3,0,1] row_mask:0xf bank_mask:0xf bound_ctrl:1
	s_waitcnt lgkmcnt(1)
	v_add_f32_e32 v33, v37, v33
	s_waitcnt lgkmcnt(0)
	v_add_f32_e32 v32, v32, v34
	v_cndmask_b32_e64 v34, v33, v32, s[2:3]
	ds_bpermute_b32 v34, v146, v34
	v_cndmask_b32_e64 v32, v32, v33, s[2:3]
	v_add_f32_dpp v35, v35, v35 row_half_mirror row_mask:0xf bank_mask:0xf bound_ctrl:1
	v_cndmask_b32_e32 v33, v48, v109, vcc
	v_cmp_eq_u32_e32 vcc, s10, v150
	s_waitcnt lgkmcnt(0)
	v_add_f32_e32 v32, v32, v34
	v_add_f32_dpp v35, v35, v35 row_mirror row_mask:0xf bank_mask:0xf bound_ctrl:1
	ds_bpermute_b32 v35, v147, v35
	v_add_f32_dpp v32, v32, v32 quad_perm:[1,0,3,2] row_mask:0xf bank_mask:0xf bound_ctrl:1
	s_waitcnt lgkmcnt(0)
	v_cndmask_b32_e32 v33, v33, v35, vcc
	v_add_f32_dpp v32, v32, v32 quad_perm:[2,3,0,1] row_mask:0xf bank_mask:0xf bound_ctrl:1
	v_cmp_eq_u32_e32 vcc, s10, v149
	s_nop 0
	v_add_f32_dpp v32, v32, v32 row_half_mirror row_mask:0xf bank_mask:0xf bound_ctrl:1
	s_nop 1
	v_add_f32_dpp v32, v32, v32 row_mirror row_mask:0xf bank_mask:0xf bound_ctrl:1
	ds_bpermute_b32 v32, v147, v32
	s_waitcnt lgkmcnt(0)
	v_cndmask_b32_e32 v107, v33, v32, vcc
	s_and_b64 vcc, exec, s[4:5]
	s_cbranch_vccnz .LBB0_891
	s_mov_b32 s10, s12
	s_branch .LBB0_887

.LBB0_898:
	s_waitcnt vmcnt(15)
	v_cvt_scalef32_pk_f32_fp4 v[116:117], v60, 1.0
	v_pk_fma_f32 v[116:117], v[116:117], v[64:65], 0 op_sel_hi:[1,1,0]
	v_cvt_scalef32_pk_f32_fp4 v[118:119], v60, 1.0 op_sel:[1,0,0]
	v_pk_fma_f32 v[116:117], v[118:119], v[66:67], v[116:117]
	v_cvt_scalef32_pk_f32_fp4 v[118:119], v60, 1.0 op_sel:[0,1,0]
	v_pk_fma_f32 v[116:117], v[118:119], v[68:69], v[116:117]
	v_cvt_scalef32_pk_f32_fp4 v[118:119], v60, 1.0 op_sel:[1,1,0]
	v_pk_fma_f32 v[116:117], v[118:119], v[70:71], v[116:117]
	v_cvt_scalef32_pk_f32_fp4 v[118:119], v61, 1.0
	v_pk_fma_f32 v[116:117], v[118:119], v[72:73], v[116:117]
	v_cvt_scalef32_pk_f32_fp4 v[118:119], v61, 1.0 op_sel:[1,0,0]
	v_pk_fma_f32 v[116:117], v[118:119], v[74:75], v[116:117]
	v_cvt_scalef32_pk_f32_fp4 v[118:119], v61, 1.0 op_sel:[0,1,0]
	v_pk_fma_f32 v[116:117], v[118:119], v[76:77], v[116:117]
	v_cvt_scalef32_pk_f32_fp4 v[60:61], v61, 1.0 op_sel:[1,1,0]
	v_pk_fma_f32 v[60:61], v[60:61], v[78:79], v[116:117]
	v_cvt_scalef32_pk_f32_fp4 v[116:117], v62, 1.0
	v_pk_fma_f32 v[60:61], v[116:117], v[80:81], v[60:61]
	v_cvt_scalef32_pk_f32_fp4 v[116:117], v62, 1.0 op_sel:[1,0,0]
	v_pk_fma_f32 v[60:61], v[116:117], v[82:83], v[60:61]
	v_cvt_scalef32_pk_f32_fp4 v[116:117], v62, 1.0 op_sel:[0,1,0]
	v_pk_fma_f32 v[60:61], v[116:117], v[84:85], v[60:61]
	v_cvt_scalef32_pk_f32_fp4 v[116:117], v62, 1.0 op_sel:[1,1,0]
	v_pk_fma_f32 v[60:61], v[116:117], v[86:87], v[60:61]
	v_cvt_scalef32_pk_f32_fp4 v[116:117], v63, 1.0
	v_pk_fma_f32 v[60:61], v[116:117], v[88:89], v[60:61]
	v_cvt_scalef32_pk_f32_fp4 v[116:117], v63, 1.0 op_sel:[1,0,0]
	v_pk_fma_f32 v[60:61], v[116:117], v[90:91], v[60:61]
	v_cvt_scalef32_pk_f32_fp4 v[116:117], v63, 1.0 op_sel:[0,1,0]
	v_pk_fma_f32 v[60:61], v[116:117], v[92:93], v[60:61]
	v_cvt_scalef32_pk_f32_fp4 v[62:63], v63, 1.0 op_sel:[1,1,0]
	v_pk_fma_f32 v[60:61], v[62:63], v[94:95], v[60:61]
	s_waitcnt vmcnt(14)
	v_cvt_scalef32_pk_f32_fp4 v[62:63], v52, 1.0 op_sel:[1,0,0]
	v_add_f32_e32 v116, v60, v61
	v_cvt_scalef32_pk_f32_fp4 v[60:61], v52, 1.0
	v_pk_fma_f32 v[60:61], v[60:61], v[64:65], 0 op_sel_hi:[1,1,0]
	v_cmp_eq_u32_e32 vcc, s10, v148
	v_pk_fma_f32 v[60:61], v[62:63], v[66:67], v[60:61]
	v_cvt_scalef32_pk_f32_fp4 v[62:63], v52, 1.0 op_sel:[0,1,0]
	v_pk_fma_f32 v[60:61], v[62:63], v[68:69], v[60:61]
	v_cvt_scalef32_pk_f32_fp4 v[62:63], v52, 1.0 op_sel:[1,1,0]
	v_pk_fma_f32 v[60:61], v[62:63], v[70:71], v[60:61]
	v_cvt_scalef32_pk_f32_fp4 v[62:63], v53, 1.0
	v_pk_fma_f32 v[60:61], v[62:63], v[72:73], v[60:61]
	v_cvt_scalef32_pk_f32_fp4 v[62:63], v53, 1.0 op_sel:[1,0,0]
	v_pk_fma_f32 v[60:61], v[62:63], v[74:75], v[60:61]
	v_cvt_scalef32_pk_f32_fp4 v[62:63], v53, 1.0 op_sel:[0,1,0]
	v_pk_fma_f32 v[60:61], v[62:63], v[76:77], v[60:61]
	v_cvt_scalef32_pk_f32_fp4 v[52:53], v53, 1.0 op_sel:[1,1,0]
	v_pk_fma_f32 v[52:53], v[52:53], v[78:79], v[60:61]
	v_cvt_scalef32_pk_f32_fp4 v[60:61], v54, 1.0
	v_pk_fma_f32 v[52:53], v[60:61], v[80:81], v[52:53]
	v_cvt_scalef32_pk_f32_fp4 v[60:61], v54, 1.0 op_sel:[1,0,0]
	v_pk_fma_f32 v[52:53], v[60:61], v[82:83], v[52:53]
	v_cvt_scalef32_pk_f32_fp4 v[60:61], v54, 1.0 op_sel:[0,1,0]
	v_pk_fma_f32 v[52:53], v[60:61], v[84:85], v[52:53]
	v_cvt_scalef32_pk_f32_fp4 v[60:61], v54, 1.0 op_sel:[1,1,0]
	v_pk_fma_f32 v[52:53], v[60:61], v[86:87], v[52:53]
	v_cvt_scalef32_pk_f32_fp4 v[60:61], v55, 1.0
	v_pk_fma_f32 v[52:53], v[60:61], v[88:89], v[52:53]
	v_cvt_scalef32_pk_f32_fp4 v[60:61], v55, 1.0 op_sel:[1,0,0]
	v_pk_fma_f32 v[52:53], v[60:61], v[90:91], v[52:53]
	v_cvt_scalef32_pk_f32_fp4 v[60:61], v55, 1.0 op_sel:[0,1,0]
	v_pk_fma_f32 v[52:53], v[60:61], v[92:93], v[52:53]
	v_cvt_scalef32_pk_f32_fp4 v[54:55], v55, 1.0 op_sel:[1,1,0]
	v_pk_fma_f32 v[52:53], v[54:55], v[94:95], v[52:53]
	s_waitcnt vmcnt(13)
	v_cvt_scalef32_pk_f32_fp4 v[54:55], v48, 1.0 op_sel:[1,0,0]
	v_add_f32_e32 v60, v52, v53
	v_cvt_scalef32_pk_f32_fp4 v[52:53], v48, 1.0
	v_pk_fma_f32 v[52:53], v[52:53], v[64:65], 0 op_sel_hi:[1,1,0]
	s_nop 0
	v_pk_fma_f32 v[52:53], v[54:55], v[66:67], v[52:53]
	v_cvt_scalef32_pk_f32_fp4 v[54:55], v48, 1.0 op_sel:[0,1,0]
	v_pk_fma_f32 v[52:53], v[54:55], v[68:69], v[52:53]
	v_cvt_scalef32_pk_f32_fp4 v[54:55], v48, 1.0 op_sel:[1,1,0]
	v_pk_fma_f32 v[52:53], v[54:55], v[70:71], v[52:53]
	v_cvt_scalef32_pk_f32_fp4 v[54:55], v49, 1.0
	v_pk_fma_f32 v[52:53], v[54:55], v[72:73], v[52:53]
	v_cvt_scalef32_pk_f32_fp4 v[54:55], v49, 1.0 op_sel:[1,0,0]
	v_pk_fma_f32 v[52:53], v[54:55], v[74:75], v[52:53]
	v_cvt_scalef32_pk_f32_fp4 v[54:55], v49, 1.0 op_sel:[0,1,0]
	v_pk_fma_f32 v[52:53], v[54:55], v[76:77], v[52:53]
	v_cvt_scalef32_pk_f32_fp4 v[48:49], v49, 1.0 op_sel:[1,1,0]
	v_pk_fma_f32 v[48:49], v[48:49], v[78:79], v[52:53]
	v_cvt_scalef32_pk_f32_fp4 v[52:53], v50, 1.0
	v_pk_fma_f32 v[48:49], v[52:53], v[80:81], v[48:49]
	v_cvt_scalef32_pk_f32_fp4 v[52:53], v50, 1.0 op_sel:[1,0,0]
	v_pk_fma_f32 v[48:49], v[52:53], v[82:83], v[48:49]
	v_cvt_scalef32_pk_f32_fp4 v[52:53], v50, 1.0 op_sel:[0,1,0]
	v_pk_fma_f32 v[48:49], v[52:53], v[84:85], v[48:49]
	v_cvt_scalef32_pk_f32_fp4 v[52:53], v50, 1.0 op_sel:[1,1,0]
	v_pk_fma_f32 v[48:49], v[52:53], v[86:87], v[48:49]
	v_cvt_scalef32_pk_f32_fp4 v[52:53], v51, 1.0
	v_pk_fma_f32 v[48:49], v[52:53], v[88:89], v[48:49]
	v_cvt_scalef32_pk_f32_fp4 v[52:53], v51, 1.0 op_sel:[1,0,0]
	v_pk_fma_f32 v[48:49], v[52:53], v[90:91], v[48:49]
	v_cvt_scalef32_pk_f32_fp4 v[52:53], v51, 1.0 op_sel:[0,1,0]
	v_pk_fma_f32 v[48:49], v[52:53], v[92:93], v[48:49]
	v_cvt_scalef32_pk_f32_fp4 v[50:51], v51, 1.0 op_sel:[1,1,0]
	v_pk_fma_f32 v[48:49], v[50:51], v[94:95], v[48:49]
	s_waitcnt vmcnt(12)
	v_cvt_scalef32_pk_f32_fp4 v[50:51], v40, 1.0 op_sel:[1,0,0]
	v_add_f32_e32 v52, v48, v49
	v_cvt_scalef32_pk_f32_fp4 v[48:49], v40, 1.0
	v_pk_fma_f32 v[48:49], v[48:49], v[64:65], 0 op_sel_hi:[1,1,0]
	s_nop 0
	v_pk_fma_f32 v[48:49], v[50:51], v[66:67], v[48:49]
	v_cvt_scalef32_pk_f32_fp4 v[50:51], v40, 1.0 op_sel:[0,1,0]
	v_pk_fma_f32 v[48:49], v[50:51], v[68:69], v[48:49]
	v_cvt_scalef32_pk_f32_fp4 v[50:51], v40, 1.0 op_sel:[1,1,0]
	v_pk_fma_f32 v[48:49], v[50:51], v[70:71], v[48:49]
	v_cvt_scalef32_pk_f32_fp4 v[50:51], v41, 1.0
	v_pk_fma_f32 v[48:49], v[50:51], v[72:73], v[48:49]
	v_cvt_scalef32_pk_f32_fp4 v[50:51], v41, 1.0 op_sel:[1,0,0]
	v_pk_fma_f32 v[48:49], v[50:51], v[74:75], v[48:49]
	v_cvt_scalef32_pk_f32_fp4 v[50:51], v41, 1.0 op_sel:[0,1,0]
	v_pk_fma_f32 v[48:49], v[50:51], v[76:77], v[48:49]
	v_cvt_scalef32_pk_f32_fp4 v[40:41], v41, 1.0 op_sel:[1,1,0]
	v_pk_fma_f32 v[40:41], v[40:41], v[78:79], v[48:49]
	v_cvt_scalef32_pk_f32_fp4 v[48:49], v42, 1.0
	v_pk_fma_f32 v[40:41], v[48:49], v[80:81], v[40:41]
	v_cvt_scalef32_pk_f32_fp4 v[48:49], v42, 1.0 op_sel:[1,0,0]
	v_pk_fma_f32 v[40:41], v[48:49], v[82:83], v[40:41]
	v_cvt_scalef32_pk_f32_fp4 v[48:49], v42, 1.0 op_sel:[0,1,0]
	v_pk_fma_f32 v[40:41], v[48:49], v[84:85], v[40:41]
	v_cvt_scalef32_pk_f32_fp4 v[48:49], v42, 1.0 op_sel:[1,1,0]
	v_pk_fma_f32 v[40:41], v[48:49], v[86:87], v[40:41]
	v_cvt_scalef32_pk_f32_fp4 v[48:49], v43, 1.0
	v_pk_fma_f32 v[40:41], v[48:49], v[88:89], v[40:41]
	v_cvt_scalef32_pk_f32_fp4 v[48:49], v43, 1.0 op_sel:[1,0,0]
	v_pk_fma_f32 v[40:41], v[48:49], v[90:91], v[40:41]
	v_cvt_scalef32_pk_f32_fp4 v[48:49], v43, 1.0 op_sel:[0,1,0]
	v_pk_fma_f32 v[40:41], v[48:49], v[92:93], v[40:41]
	v_cvt_scalef32_pk_f32_fp4 v[42:43], v43, 1.0 op_sel:[1,1,0]
	v_pk_fma_f32 v[40:41], v[42:43], v[94:95], v[40:41]
	v_cndmask_b32_e64 v43, v52, v116, s[0:1]
	v_add_f32_e32 v40, v40, v41
	v_cndmask_b32_e64 v41, v116, v52, s[0:1]
	v_cndmask_b32_e64 v42, v60, v40, s[0:1]
	ds_bpermute_b32 v41, v129, v41
	ds_bpermute_b32 v42, v129, v42
	v_cndmask_b32_e64 v40, v40, v60, s[0:1]
	s_waitcnt lgkmcnt(3)
	v_cndmask_b32_e32 v48, v109, v115, vcc
	v_cmp_eq_u32_e32 vcc, s10, v151
	s_waitcnt lgkmcnt(1)
	v_add_f32_e32 v41, v43, v41
	s_waitcnt lgkmcnt(0)
	v_add_f32_e32 v40, v40, v42
	v_cndmask_b32_e64 v42, v41, v40, s[2:3]
	ds_bpermute_b32 v42, v146, v42
	v_cndmask_b32_e64 v40, v40, v41, s[2:3]
	s_waitcnt lgkmcnt(0)
	v_add_f32_e32 v40, v40, v42
	s_nop 1
	v_add_f32_dpp v40, v40, v40 quad_perm:[1,0,3,2] row_mask:0xf bank_mask:0xf bound_ctrl:1
	s_waitcnt vmcnt(11)
	v_cvt_scalef32_pk_f32_fp4 v[42:43], v36, 1.0 op_sel:[1,0,0]
	v_add_f32_dpp v40, v40, v40 quad_perm:[2,3,0,1] row_mask:0xf bank_mask:0xf bound_ctrl:1
	s_nop 1
	v_add_f32_dpp v40, v40, v40 row_half_mirror row_mask:0xf bank_mask:0xf bound_ctrl:1
	s_nop 1
	v_add_f32_dpp v49, v40, v40 row_mirror row_mask:0xf bank_mask:0xf bound_ctrl:1
	v_cvt_scalef32_pk_f32_fp4 v[40:41], v36, 1.0
	v_pk_fma_f32 v[40:41], v[40:41], v[64:65], 0 op_sel_hi:[1,1,0]
	s_nop 0
	v_pk_fma_f32 v[40:41], v[42:43], v[66:67], v[40:41]
	v_cvt_scalef32_pk_f32_fp4 v[42:43], v36, 1.0 op_sel:[0,1,0]
	v_pk_fma_f32 v[40:41], v[42:43], v[68:69], v[40:41]
	v_cvt_scalef32_pk_f32_fp4 v[42:43], v36, 1.0 op_sel:[1,1,0]
	v_pk_fma_f32 v[40:41], v[42:43], v[70:71], v[40:41]
	v_cvt_scalef32_pk_f32_fp4 v[42:43], v37, 1.0
	v_pk_fma_f32 v[40:41], v[42:43], v[72:73], v[40:41]
	v_cvt_scalef32_pk_f32_fp4 v[42:43], v37, 1.0 op_sel:[1,0,0]
	v_pk_fma_f32 v[40:41], v[42:43], v[74:75], v[40:41]
	v_cvt_scalef32_pk_f32_fp4 v[42:43], v37, 1.0 op_sel:[0,1,0]
	v_pk_fma_f32 v[40:41], v[42:43], v[76:77], v[40:41]
	v_cvt_scalef32_pk_f32_fp4 v[36:37], v37, 1.0 op_sel:[1,1,0]
	v_pk_fma_f32 v[36:37], v[36:37], v[78:79], v[40:41]
	v_cvt_scalef32_pk_f32_fp4 v[40:41], v38, 1.0
	v_pk_fma_f32 v[36:37], v[40:41], v[80:81], v[36:37]
	v_cvt_scalef32_pk_f32_fp4 v[40:41], v38, 1.0 op_sel:[1,0,0]
	v_pk_fma_f32 v[36:37], v[40:41], v[82:83], v[36:37]
	v_cvt_scalef32_pk_f32_fp4 v[40:41], v38, 1.0 op_sel:[0,1,0]
	v_pk_fma_f32 v[36:37], v[40:41], v[84:85], v[36:37]
	v_cvt_scalef32_pk_f32_fp4 v[40:41], v38, 1.0 op_sel:[1,1,0]
	v_pk_fma_f32 v[36:37], v[40:41], v[86:87], v[36:37]
	v_cvt_scalef32_pk_f32_fp4 v[40:41], v39, 1.0
	v_pk_fma_f32 v[36:37], v[40:41], v[88:89], v[36:37]
	v_cvt_scalef32_pk_f32_fp4 v[40:41], v39, 1.0 op_sel:[1,0,0]
	v_pk_fma_f32 v[36:37], v[40:41], v[90:91], v[36:37]
	v_cvt_scalef32_pk_f32_fp4 v[40:41], v39, 1.0 op_sel:[0,1,0]
	v_pk_fma_f32 v[36:37], v[40:41], v[92:93], v[36:37]
	v_cvt_scalef32_pk_f32_fp4 v[38:39], v39, 1.0 op_sel:[1,1,0]
	v_pk_fma_f32 v[36:37], v[38:39], v[94:95], v[36:37]
	s_waitcnt vmcnt(10)
	v_cvt_scalef32_pk_f32_fp4 v[38:39], v32, 1.0 op_sel:[1,0,0]
	v_add_f32_e32 v40, v36, v37
	v_cvt_scalef32_pk_f32_fp4 v[36:37], v32, 1.0
	v_pk_fma_f32 v[36:37], v[36:37], v[64:65], 0 op_sel_hi:[1,1,0]
	s_nop 0
	v_pk_fma_f32 v[36:37], v[38:39], v[66:67], v[36:37]
	v_cvt_scalef32_pk_f32_fp4 v[38:39], v32, 1.0 op_sel:[0,1,0]
	v_pk_fma_f32 v[36:37], v[38:39], v[68:69], v[36:37]
	v_cvt_scalef32_pk_f32_fp4 v[38:39], v32, 1.0 op_sel:[1,1,0]
	v_pk_fma_f32 v[36:37], v[38:39], v[70:71], v[36:37]
	v_cvt_scalef32_pk_f32_fp4 v[38:39], v33, 1.0
	v_pk_fma_f32 v[36:37], v[38:39], v[72:73], v[36:37]
	v_cvt_scalef32_pk_f32_fp4 v[38:39], v33, 1.0 op_sel:[1,0,0]
	v_pk_fma_f32 v[36:37], v[38:39], v[74:75], v[36:37]
	v_cvt_scalef32_pk_f32_fp4 v[38:39], v33, 1.0 op_sel:[0,1,0]
	v_pk_fma_f32 v[36:37], v[38:39], v[76:77], v[36:37]
	v_cvt_scalef32_pk_f32_fp4 v[32:33], v33, 1.0 op_sel:[1,1,0]
	v_pk_fma_f32 v[32:33], v[32:33], v[78:79], v[36:37]
	v_cvt_scalef32_pk_f32_fp4 v[36:37], v34, 1.0
	v_pk_fma_f32 v[32:33], v[36:37], v[80:81], v[32:33]
	v_cvt_scalef32_pk_f32_fp4 v[36:37], v34, 1.0 op_sel:[1,0,0]
	v_pk_fma_f32 v[32:33], v[36:37], v[82:83], v[32:33]
	v_cvt_scalef32_pk_f32_fp4 v[36:37], v34, 1.0 op_sel:[0,1,0]
	v_pk_fma_f32 v[32:33], v[36:37], v[84:85], v[32:33]
	v_cvt_scalef32_pk_f32_fp4 v[36:37], v34, 1.0 op_sel:[1,1,0]
	v_pk_fma_f32 v[32:33], v[36:37], v[86:87], v[32:33]
	v_cvt_scalef32_pk_f32_fp4 v[36:37], v35, 1.0
	v_pk_fma_f32 v[32:33], v[36:37], v[88:89], v[32:33]
	v_cvt_scalef32_pk_f32_fp4 v[36:37], v35, 1.0 op_sel:[1,0,0]
	v_pk_fma_f32 v[32:33], v[36:37], v[90:91], v[32:33]
	v_cvt_scalef32_pk_f32_fp4 v[36:37], v35, 1.0 op_sel:[0,1,0]
	v_pk_fma_f32 v[32:33], v[36:37], v[92:93], v[32:33]
	v_cvt_scalef32_pk_f32_fp4 v[34:35], v35, 1.0 op_sel:[1,1,0]
	v_pk_fma_f32 v[32:33], v[34:35], v[94:95], v[32:33]
	s_waitcnt vmcnt(9)
; #define PU_LOAD(BUF, EV, S0) do { _Pragma("unroll") for (int i = 0; i < 8; ++i) { const int row_ = __builtin_amdgcn_readlane(EV, (S0) + i); BUF[i & 3][i >> 2] = *(const u32x4*)(PU8 + (size_t)row_ * 1024 + lane * 16); } } while (0)
; __global__ void __launch_bounds__(NT, 2) mk_fwd(Args args) {
;     ...
;                 for (int s = 0; s < 64; s += 16) {
;                     PU_LOAD(bB, ev, s + 8);
;                     PU_DOT4(bA, 0, s); PU_DOT4(bA, 1, s + 4);
;                     if (s + 16 < 64) PU_LOAD(bA, ev, s + 16);
;                     PU_DOT4(bB, 0, s + 8); PU_DOT4(bB, 1, s + 12);
;                 }
	v_cvt_scalef32_pk_f32_fp4 v[34:35], v56, 1.0 op_sel:[1,0,0]
	v_add_f32_e32 v36, v32, v33
	v_cvt_scalef32_pk_f32_fp4 v[32:33], v56, 1.0
	v_pk_fma_f32 v[32:33], v[32:33], v[64:65], 0 op_sel_hi:[1,1,0]
	s_nop 0
	v_pk_fma_f32 v[32:33], v[34:35], v[66:67], v[32:33]
	v_cvt_scalef32_pk_f32_fp4 v[34:35], v56, 1.0 op_sel:[0,1,0]
	v_pk_fma_f32 v[32:33], v[34:35], v[68:69], v[32:33]
	v_cvt_scalef32_pk_f32_fp4 v[34:35], v56, 1.0 op_sel:[1,1,0]
	v_pk_fma_f32 v[32:33], v[34:35], v[70:71], v[32:33]
	v_cvt_scalef32_pk_f32_fp4 v[34:35], v57, 1.0
	v_pk_fma_f32 v[32:33], v[34:35], v[72:73], v[32:33]
	v_cvt_scalef32_pk_f32_fp4 v[34:35], v57, 1.0 op_sel:[1,0,0]
	v_pk_fma_f32 v[32:33], v[34:35], v[74:75], v[32:33]
	v_cvt_scalef32_pk_f32_fp4 v[34:35], v57, 1.0 op_sel:[0,1,0]
	v_pk_fma_f32 v[32:33], v[34:35], v[76:77], v[32:33]
	v_cvt_scalef32_pk_f32_fp4 v[34:35], v57, 1.0 op_sel:[1,1,0]
	v_pk_fma_f32 v[32:33], v[34:35], v[78:79], v[32:33]
	v_cvt_scalef32_pk_f32_fp4 v[34:35], v58, 1.0
	v_pk_fma_f32 v[32:33], v[34:35], v[80:81], v[32:33]
	v_cvt_scalef32_pk_f32_fp4 v[34:35], v58, 1.0 op_sel:[1,0,0]
	v_pk_fma_f32 v[32:33], v[34:35], v[82:83], v[32:33]
	v_cvt_scalef32_pk_f32_fp4 v[34:35], v58, 1.0 op_sel:[0,1,0]
	v_pk_fma_f32 v[32:33], v[34:35], v[84:85], v[32:33]
	v_cvt_scalef32_pk_f32_fp4 v[34:35], v58, 1.0 op_sel:[1,1,0]
	v_pk_fma_f32 v[32:33], v[34:35], v[86:87], v[32:33]
	v_cvt_scalef32_pk_f32_fp4 v[34:35], v59, 1.0
	v_pk_fma_f32 v[32:33], v[34:35], v[88:89], v[32:33]
	v_cvt_scalef32_pk_f32_fp4 v[34:35], v59, 1.0 op_sel:[1,0,0]
	v_pk_fma_f32 v[32:33], v[34:35], v[90:91], v[32:33]
	v_cvt_scalef32_pk_f32_fp4 v[34:35], v59, 1.0 op_sel:[0,1,0]
	v_pk_fma_f32 v[32:33], v[34:35], v[92:93], v[32:33]
	v_cvt_scalef32_pk_f32_fp4 v[34:35], v59, 1.0 op_sel:[1,1,0]
	v_pk_fma_f32 v[32:33], v[34:35], v[94:95], v[32:33]
	s_waitcnt vmcnt(8)
	v_cvt_scalef32_pk_f32_fp4 v[34:35], v44, 1.0 op_sel:[1,0,0]
	v_add_f32_e32 v37, v32, v33
	v_cvt_scalef32_pk_f32_fp4 v[32:33], v44, 1.0
	v_pk_fma_f32 v[32:33], v[32:33], v[64:65], 0 op_sel_hi:[1,1,0]
	s_nop 0
	v_pk_fma_f32 v[32:33], v[34:35], v[66:67], v[32:33]
	v_cvt_scalef32_pk_f32_fp4 v[34:35], v44, 1.0 op_sel:[0,1,0]
	v_pk_fma_f32 v[32:33], v[34:35], v[68:69], v[32:33]
	v_cvt_scalef32_pk_f32_fp4 v[34:35], v44, 1.0 op_sel:[1,1,0]
	v_pk_fma_f32 v[32:33], v[34:35], v[70:71], v[32:33]
	v_cvt_scalef32_pk_f32_fp4 v[34:35], v45, 1.0
	v_pk_fma_f32 v[32:33], v[34:35], v[72:73], v[32:33]
	v_cvt_scalef32_pk_f32_fp4 v[34:35], v45, 1.0 op_sel:[1,0,0]
	v_pk_fma_f32 v[32:33], v[34:35], v[74:75], v[32:33]
	v_cvt_scalef32_pk_f32_fp4 v[34:35], v45, 1.0 op_sel:[0,1,0]
	v_pk_fma_f32 v[32:33], v[34:35], v[76:77], v[32:33]
	v_cvt_scalef32_pk_f32_fp4 v[34:35], v45, 1.0 op_sel:[1,1,0]
	v_pk_fma_f32 v[32:33], v[34:35], v[78:79], v[32:33]
	v_cvt_scalef32_pk_f32_fp4 v[34:35], v46, 1.0
	v_pk_fma_f32 v[32:33], v[34:35], v[80:81], v[32:33]
	v_cvt_scalef32_pk_f32_fp4 v[34:35], v46, 1.0 op_sel:[1,0,0]
	v_pk_fma_f32 v[32:33], v[34:35], v[82:83], v[32:33]
	v_cvt_scalef32_pk_f32_fp4 v[34:35], v46, 1.0 op_sel:[0,1,0]
	v_pk_fma_f32 v[32:33], v[34:35], v[84:85], v[32:33]
	v_cvt_scalef32_pk_f32_fp4 v[34:35], v46, 1.0 op_sel:[1,1,0]
	v_pk_fma_f32 v[32:33], v[34:35], v[86:87], v[32:33]
	v_cvt_scalef32_pk_f32_fp4 v[34:35], v47, 1.0
	v_pk_fma_f32 v[32:33], v[34:35], v[88:89], v[32:33]
	v_cvt_scalef32_pk_f32_fp4 v[34:35], v47, 1.0 op_sel:[1,0,0]
	v_pk_fma_f32 v[32:33], v[34:35], v[90:91], v[32:33]
	v_cvt_scalef32_pk_f32_fp4 v[34:35], v47, 1.0 op_sel:[0,1,0]
	v_pk_fma_f32 v[32:33], v[34:35], v[92:93], v[32:33]
	v_cvt_scalef32_pk_f32_fp4 v[34:35], v47, 1.0 op_sel:[1,1,0]
	v_pk_fma_f32 v[32:33], v[34:35], v[94:95], v[32:33]
	ds_bpermute_b32 v35, v147, v49
	v_add_f32_e32 v32, v32, v33
	v_cndmask_b32_e64 v33, v40, v37, s[0:1]
	v_cndmask_b32_e64 v34, v36, v32, s[0:1]
	ds_bpermute_b32 v33, v129, v33
	ds_bpermute_b32 v34, v129, v34
	v_cndmask_b32_e64 v37, v37, v40, s[0:1]
	v_cndmask_b32_e64 v32, v32, v36, s[0:1]
	v_cndmask_b32_e32 v36, v48, v107, vcc
	s_waitcnt lgkmcnt(1)
	v_add_f32_e32 v33, v37, v33
	s_waitcnt lgkmcnt(0)
	v_add_f32_e32 v32, v32, v34
	v_cndmask_b32_e64 v34, v33, v32, s[2:3]
	ds_bpermute_b32 v34, v146, v34
	v_cndmask_b32_e64 v32, v32, v33, s[2:3]
	v_cmp_eq_u32_e32 vcc, s10, v150
	s_waitcnt lgkmcnt(0)
	v_add_f32_e32 v32, v32, v34
	s_nop 1
	v_add_f32_dpp v32, v32, v32 quad_perm:[1,0,3,2] row_mask:0xf bank_mask:0xf bound_ctrl:1
	v_cndmask_b32_e32 v35, v36, v35, vcc
	s_andn2_b64 vcc, exec, s[4:5]
	v_add_f32_dpp v32, v32, v32 quad_perm:[2,3,0,1] row_mask:0xf bank_mask:0xf bound_ctrl:1
	v_cmp_eq_u32_e64 s[4:5], s10, v149
	s_nop 0
	v_add_f32_dpp v32, v32, v32 row_half_mirror row_mask:0xf bank_mask:0xf bound_ctrl:1
	s_nop 1
	v_add_f32_dpp v32, v32, v32 row_mirror row_mask:0xf bank_mask:0xf bound_ctrl:1
	ds_bpermute_b32 v32, v147, v32
	s_waitcnt lgkmcnt(0)
	v_cndmask_b32_e64 v109, v35, v32, s[4:5]
	s_cbranch_vccz .LBB0_900
	s_mov_b32 s10, s12
	s_branch .LBB0_896
